# attention loop: LDS-DMA pieces issued behind MFMAs 2, 4, 6, 8 of the score phase
# baseline (speedup 1.0000x reference)
; #define MFMA32(a, b, c) __builtin_amdgcn_mfma_f32_32x32x16_bf16((a), (b), (c), 0, 0, 0)
; #define WAIT_BAR0() asm volatile("s_waitcnt vmcnt(0) lgkmcnt(0)\n\ts_barrier" ::: "memory")
; #define DMA_TILE(kt_, so_) do { glds16(kgp + (size_t)(kt_) * 64 * 128, dk0 + (so_)); glds16(kgp + (size_t)(kt_) * 64 * 128 + 32 * 128, dk0 + (so_) + 8192); \
;     glds16(vgp + (kt_) * 64, dk0 + (so_) + 16384); glds16(vgp + (size_t)64 * SEQ + (kt_) * 64, dk0 + (so_) + 24576); } while (0)
; #define SOFTMAX_PACK(S_, P_, l_) do { _Pragma("unroll") for (int e = 0; e < 16; ++e) { S_[e] = __builtin_amdgcn_exp2f(S_[e]); l_ += S_[e]; } \
;         _Pragma("unroll") for (int s = 0; s < 2; ++s) { u32x4 a_; _Pragma("unroll") for (int q = 0; q < 4; ++q) a_[q] = cvtpk(S_[8 * s + 2 * q], S_[8 * s + 2 * q + 1]); P_[s] = __builtin_bit_cast(bf16x8, a_); } } while (0)
; DI void attn_item(const Params& p, char* lds, int l, int bh, int jt, float lam, float outscale) {
;     ...
;   for (int kt = 0; kt < nkt; ++kt) {
;     WAIT_BAR0();
;     const unsigned so = (kt & 1) * 32768;
;     if (kt + 1 < nkt) DMA_TILE(kt + 1, 32768 - so);
;     if (kt <= my_last) {
;     ...
;       bf16x8 pa0[2], pa1[2];
;       f32x16 S0, S1;
; #pragma unroll
;       for (int e = 0; e < 16; ++e) { S0[e] = 0.f; S1[e] = 0.f; }
; #pragma unroll
;       for (int ks = 0; ks < 4; ++ks) {
;         S0 = MFMA32(KFRAG(0, 0, ks), QFRAG(0, ks), S0);
;         S1 = MFMA32(KFRAG(0, 1, ks), QFRAG(1, ks), S1);
;       }
;       SOFTMAX_PACK(S0, pa0, l0);
;       SOFTMAX_PACK(S1, pa1, l1);
; #pragma unroll
;       for (int e = 0; e < 16; ++e) { S0[e] = 0.f; S1[e] = 0.f; }
; #pragma unroll
;       for (int ks = 0; ks < 4; ++ks) {
;         S0 = MFMA32(KFRAG(1, 0, ks), QFRAG(0, ks), S0);
;         S1 = MFMA32(KFRAG(1, 1, ks), QFRAG(1, ks), S1);
; #pragma unroll
;         for (int dd = 0; dd < 2; ++dd) {
;           const int d = (ks & 1) * 2 + dd, s = ks >> 1;
;           const bf16x8 vf = VFRAG(0, d, s);
;           O0[d] = MFMA32(vf, pa0[s], O0[d]);
;           O1[d] = MFMA32(vf, pa1[s], O1[d]);
;         }
.Lattn_nodefer:
	s_waitcnt lgkmcnt(6)
	v_mfma_f32_32x32x16_bf16 v[144:159], v[160:163], v[226:229], 0
	ds_read_b128 v[210:213], v251
	ds_read_b128 v[160:163], v235
	s_waitcnt lgkmcnt(6)
	v_mfma_f32_32x32x16_bf16 v[144:159], v[164:167], v[230:233], v[144:159]
	ds_read_b128 v[214:217], v251 offset:8192
	ds_read_b128 v[164:167], v236
	s_cmp_ge_i32 s27, s24
	s_cbranch_scc1 .Ldma_skip_1
	s_mov_b32 m0, s54
	s_nop 0
	global_load_lds_dwordx4 v208, s[50:51]
.Ldma_skip_1:
	s_waitcnt lgkmcnt(6)
	v_mfma_f32_32x32x16_bf16 v[144:159], v[168:171], v[240:243], v[144:159]
	ds_read_b128 v[218:221], v251 offset:16384
	ds_read_b128 v[168:171], v237
	s_waitcnt lgkmcnt(6)
	v_mfma_f32_32x32x16_bf16 v[144:159], v[172:175], v[192:195], v[144:159]
	ds_read_b128 v[222:225], v251 offset:24576
	ds_read_b128 v[172:175], v244
	s_cmp_ge_i32 s27, s24
	s_cbranch_scc1 .Ldma_skip_2
	s_add_u32 s50, s50, 0x2000
	s_addc_u32 s51, s51, 0
	s_add_i32 s54, s54, 0x2000
	s_mov_b32 m0, s54
	s_nop 0
	global_load_lds_dwordx4 v208, s[50:51]
.Ldma_skip_2:
	s_waitcnt lgkmcnt(6)
	v_mfma_f32_32x32x16_bf16 v[128:143], v[160:163], v[210:213], 0
	ds_read_b128 v[176:179], v203 offset:8192
	v_exp_f32_e32 v144, v144
	v_exp_f32_e32 v145, v145
	v_add_f32_e32 v207, v207, v144
	v_add_f32_e32 v207, v207, v145
	s_waitcnt lgkmcnt(5)
	v_mfma_f32_32x32x16_bf16 v[128:143], v[164:167], v[214:217], v[128:143]
	ds_read_b128 v[180:183], v204 offset:8192
	s_cmp_ge_i32 s27, s24
	s_cbranch_scc1 .Ldma_skip_3
	s_add_i32 s54, s54, 0x2000
	s_mov_b32 m0, s54
	s_nop 0
	global_load_lds_dwordx4 v202, s[52:53]
.Ldma_skip_3:
	v_cvt_pk_bf16_f32 v144, v144, v145
	v_exp_f32_e32 v146, v146
	v_exp_f32_e32 v147, v147
	v_add_f32_e32 v207, v207, v146
	s_waitcnt lgkmcnt(4)
	v_mfma_f32_32x32x16_bf16 v[128:143], v[168:171], v[218:221], v[128:143]
	ds_read_b128 v[184:187], v205 offset:8192
	v_add_f32_e32 v207, v207, v147
	v_cvt_pk_bf16_f32 v145, v146, v147
	v_exp_f32_e32 v148, v148
	v_exp_f32_e32 v149, v149
	s_waitcnt lgkmcnt(3)
	v_mfma_f32_32x32x16_bf16 v[128:143], v[172:175], v[222:225], v[128:143]
	ds_read_b128 v[188:191], v209 offset:8192
	s_cmp_ge_i32 s27, s24
	s_cbranch_scc1 .Ldma_skip_4
	s_add_u32 s52, s52, 0x200000
	s_addc_u32 s53, s53, 0
	s_add_i32 s54, s54, 0x2000
	s_mov_b32 m0, s54
	s_nop 0
	global_load_lds_dwordx4 v202, s[52:53]
.Ldma_skip_4:
	v_add_f32_e32 v207, v207, v148
	v_add_f32_e32 v207, v207, v149
	v_cvt_pk_bf16_f32 v146, v148, v149
	v_exp_f32_e32 v150, v150
	s_waitcnt lgkmcnt(3)
	v_mfma_f32_32x32x16_bf16 v[160:175], v[176:179], v[226:229], 0
	ds_read_b128 v[226:229], v235 offset:8192
	v_exp_f32_e32 v151, v151
	v_add_f32_e32 v207, v207, v150
	v_add_f32_e32 v207, v207, v151
	v_cvt_pk_bf16_f32 v147, v150, v151
	s_waitcnt lgkmcnt(3)
	v_mfma_f32_32x32x16_bf16 v[160:175], v[180:183], v[230:233], v[160:175]
	ds_read_b128 v[230:233], v236 offset:8192
	v_exp_f32_e32 v128, v128
	v_exp_f32_e32 v129, v129
	v_add_f32_e32 v206, v206, v128
	v_add_f32_e32 v206, v206, v129
	s_waitcnt lgkmcnt(3)
	v_mfma_f32_32x32x16_bf16 v[160:175], v[184:187], v[240:243], v[160:175]
	ds_read_b128 v[240:243], v237 offset:8192
	v_cvt_pk_bf16_f32 v128, v128, v129
	v_exp_f32_e32 v130, v130
	v_exp_f32_e32 v131, v131
	v_add_f32_e32 v206, v206, v130
	s_waitcnt lgkmcnt(3)
	v_mfma_f32_32x32x16_bf16 v[160:175], v[188:191], v[192:195], v[160:175]
	ds_read_b128 v[192:195], v244 offset:8192
	v_add_f32_e32 v206, v206, v131
	v_cvt_pk_bf16_f32 v129, v130, v131
	v_exp_f32_e32 v132, v132
	v_exp_f32_e32 v133, v133
	v_add_u32_e32 v203, s49, v253
	v_xor_b32_e32 v204, 0x20, v203
	v_xor_b32_e32 v205, 0x40, v203
	v_xor_b32_e32 v209, 0x60, v203
	s_waitcnt lgkmcnt(3)
	v_mfma_f32_32x32x16_bf16 v[176:191], v[226:229], v[210:213], 0
	ds_read_b128 v[226:229], v203 offset:16384
	v_add_f32_e32 v206, v206, v132
	v_add_f32_e32 v206, v206, v133
	v_cvt_pk_bf16_f32 v130, v132, v133
	v_exp_f32_e32 v134, v134
	s_waitcnt lgkmcnt(3)
	v_mfma_f32_32x32x16_bf16 v[176:191], v[230:233], v[214:217], v[176:191]
	ds_read_b128 v[230:233], v203 offset:20480
	v_exp_f32_e32 v135, v135
	v_add_f32_e32 v206, v206, v134
	v_add_f32_e32 v206, v206, v135
	v_cvt_pk_bf16_f32 v131, v134, v135
	s_waitcnt lgkmcnt(3)
	v_mfma_f32_32x32x16_bf16 v[176:191], v[240:243], v[218:221], v[176:191]
	ds_read_b128 v[240:243], v203 offset:24576
	v_exp_f32_e32 v152, v152
	v_exp_f32_e32 v153, v153
	v_add_f32_e32 v207, v207, v152
	v_add_f32_e32 v207, v207, v153
	s_waitcnt lgkmcnt(3)
	v_mfma_f32_32x32x16_bf16 v[176:191], v[192:195], v[222:225], v[176:191]
	ds_read_b128 v[192:195], v203 offset:28672
	v_cvt_pk_bf16_f32 v148, v152, v153
	v_exp_f32_e32 v154, v154
	v_exp_f32_e32 v155, v155
	v_add_f32_e32 v207, v207, v154
	s_waitcnt lgkmcnt(3)
	v_mfma_f32_32x32x16_bf16 v[112:127], v[226:229], v[144:147], v[112:127]
	ds_read_b128 v[210:213], v204 offset:16384
	v_add_f32_e32 v207, v207, v155
	v_cvt_pk_bf16_f32 v149, v154, v155
	v_exp_f32_e32 v156, v156
	v_exp_f32_e32 v157, v157
	s_waitcnt lgkmcnt(3)
	v_mfma_f32_32x32x16_bf16 v[64:79], v[230:233], v[144:147], v[64:79]
	ds_read_b128 v[214:217], v204 offset:20480
	v_add_f32_e32 v207, v207, v156
	v_add_f32_e32 v207, v207, v157
	v_cvt_pk_bf16_f32 v150, v156, v157
	v_exp_f32_e32 v158, v158
	s_waitcnt lgkmcnt(3)
	v_mfma_f32_32x32x16_bf16 v[32:47], v[240:243], v[144:147], v[32:47]
	ds_read_b128 v[218:221], v204 offset:24576
	v_exp_f32_e32 v159, v159
	v_add_f32_e32 v207, v207, v158
	v_add_f32_e32 v207, v207, v159
	v_cvt_pk_bf16_f32 v151, v158, v159
	s_waitcnt lgkmcnt(3)
; #define MFMA32(a, b, c) __builtin_amdgcn_mfma_f32_32x32x16_bf16((a), (b), (c), 0, 0, 0)
; #define SOFTMAX_PACK(S_, P_, l_) do { _Pragma("unroll") for (int e = 0; e < 16; ++e) { S_[e] = __builtin_amdgcn_exp2f(S_[e]); l_ += S_[e]; } \
;         _Pragma("unroll") for (int s = 0; s < 2; ++s) { u32x4 a_; _Pragma("unroll") for (int q = 0; q < 4; ++q) a_[q] = cvtpk(S_[8 * s + 2 * q], S_[8 * s + 2 * q + 1]); P_[s] = __builtin_bit_cast(bf16x8, a_); } } while (0)
; DI void attn_item(const Params& p, char* lds, int l, int bh, int jt, float lam, float outscale) {
;     ...
;       SOFTMAX_PACK(S0, pa0, l0);
;       SOFTMAX_PACK(S1, pa1, l1);
; #pragma unroll
;       for (int e = 0; e < 16; ++e) { S0[e] = 0.f; S1[e] = 0.f; }
; #pragma unroll
;       for (int ks = 0; ks < 4; ++ks) {
;         S0 = MFMA32(KFRAG(1, 0, ks), QFRAG(0, ks), S0);
;         S1 = MFMA32(KFRAG(1, 1, ks), QFRAG(1, ks), S1);
; #pragma unroll
;         for (int dd = 0; dd < 2; ++dd) {
;           const int d = (ks & 1) * 2 + dd, s = ks >> 1;
;           const bf16x8 vf = VFRAG(0, d, s);
;           O0[d] = MFMA32(vf, pa0[s], O0[d]);
;           O1[d] = MFMA32(vf, pa1[s], O1[d]);
;         }
;       }
;       bf16x8 pc0[2], pc1[2];
;       SOFTMAX_PACK(S0, pc0, l0);
;       SOFTMAX_PACK(S1, pc1, l1);
; #pragma unroll
;       for (int s = 0; s < 2; ++s) {
; #pragma unroll
;         for (int d = 0; d < 4; ++d) {
;           const bf16x8 vf = VFRAG(1, d, s);
;           O0[d] = MFMA32(vf, pc0[s], O0[d]);
;           O1[d] = MFMA32(vf, pc1[s], O1[d]);
;         }
	v_mfma_f32_32x32x16_bf16 v[0:15], v[192:195], v[144:147], v[0:15]
	ds_read_b128 v[222:225], v204 offset:28672
	v_exp_f32_e32 v136, v136
	v_exp_f32_e32 v137, v137
	v_add_f32_e32 v206, v206, v136
	v_add_f32_e32 v206, v206, v137
	v_mfma_f32_32x32x16_bf16 v[96:111], v[226:229], v[128:131], v[96:111]
	v_cvt_pk_bf16_f32 v132, v136, v137
	v_exp_f32_e32 v138, v138
	v_exp_f32_e32 v139, v139
	v_add_f32_e32 v206, v206, v138
	v_mfma_f32_32x32x16_bf16 v[80:95], v[230:233], v[128:131], v[80:95]
	v_add_f32_e32 v206, v206, v139
	v_cvt_pk_bf16_f32 v133, v138, v139
	v_exp_f32_e32 v140, v140
	v_exp_f32_e32 v141, v141
	v_mfma_f32_32x32x16_bf16 v[48:63], v[240:243], v[128:131], v[48:63]
	v_add_f32_e32 v206, v206, v140
	v_add_f32_e32 v206, v206, v141
	v_cvt_pk_bf16_f32 v134, v140, v141
	v_exp_f32_e32 v142, v142
	v_mfma_f32_32x32x16_bf16 v[16:31], v[192:195], v[128:131], v[16:31]
	v_exp_f32_e32 v143, v143
	v_add_f32_e32 v206, v206, v142
	v_add_f32_e32 v206, v206, v143
	v_cvt_pk_bf16_f32 v135, v142, v143
	s_waitcnt lgkmcnt(3)
	v_mfma_f32_32x32x16_bf16 v[112:127], v[210:213], v[148:151], v[112:127]
	ds_read_b128 v[226:229], v205 offset:16384
	v_exp_f32_e32 v160, v160
	v_exp_f32_e32 v161, v161
	v_add_f32_e32 v207, v207, v160
	v_add_f32_e32 v207, v207, v161
	s_waitcnt lgkmcnt(3)
	v_mfma_f32_32x32x16_bf16 v[64:79], v[214:217], v[148:151], v[64:79]
	ds_read_b128 v[230:233], v205 offset:20480
	v_cvt_pk_bf16_f32 v160, v160, v161
	v_exp_f32_e32 v162, v162
	v_exp_f32_e32 v163, v163
	v_add_f32_e32 v207, v207, v162
	s_waitcnt lgkmcnt(3)
	v_mfma_f32_32x32x16_bf16 v[32:47], v[218:221], v[148:151], v[32:47]
	ds_read_b128 v[240:243], v205 offset:24576
	v_add_f32_e32 v207, v207, v163
	v_cvt_pk_bf16_f32 v161, v162, v163
	v_exp_f32_e32 v164, v164
	v_exp_f32_e32 v165, v165
	s_waitcnt lgkmcnt(3)
	v_mfma_f32_32x32x16_bf16 v[0:15], v[222:225], v[148:151], v[0:15]
	ds_read_b128 v[192:195], v205 offset:28672
	v_add_f32_e32 v207, v207, v164
	v_add_f32_e32 v207, v207, v165
	v_cvt_pk_bf16_f32 v162, v164, v165
	v_exp_f32_e32 v166, v166
	v_mfma_f32_32x32x16_bf16 v[96:111], v[210:213], v[132:135], v[96:111]
	v_exp_f32_e32 v167, v167
	v_add_f32_e32 v207, v207, v166
	v_add_f32_e32 v207, v207, v167
	v_cvt_pk_bf16_f32 v163, v166, v167
	v_mfma_f32_32x32x16_bf16 v[80:95], v[214:217], v[132:135], v[80:95]
	v_exp_f32_e32 v176, v176
	v_exp_f32_e32 v177, v177
	v_add_f32_e32 v206, v206, v176
	v_add_f32_e32 v206, v206, v177
	v_mfma_f32_32x32x16_bf16 v[48:63], v[218:221], v[132:135], v[48:63]
	v_cvt_pk_bf16_f32 v176, v176, v177
	v_exp_f32_e32 v178, v178
	v_exp_f32_e32 v179, v179
	v_add_f32_e32 v206, v206, v178
	v_mfma_f32_32x32x16_bf16 v[16:31], v[222:225], v[132:135], v[16:31]
	v_add_f32_e32 v206, v206, v179
	v_cvt_pk_bf16_f32 v177, v178, v179
	v_exp_f32_e32 v180, v180
	v_exp_f32_e32 v181, v181
	s_waitcnt lgkmcnt(3)
	v_mfma_f32_32x32x16_bf16 v[112:127], v[226:229], v[160:163], v[112:127]
	ds_read_b128 v[210:213], v209 offset:16384
	v_add_f32_e32 v206, v206, v180
	v_add_f32_e32 v206, v206, v181
	v_cvt_pk_bf16_f32 v178, v180, v181
	v_exp_f32_e32 v182, v182
	s_waitcnt lgkmcnt(3)
	v_mfma_f32_32x32x16_bf16 v[64:79], v[230:233], v[160:163], v[64:79]
	ds_read_b128 v[214:217], v209 offset:20480
	v_exp_f32_e32 v183, v183
	v_add_f32_e32 v206, v206, v182
	v_add_f32_e32 v206, v206, v183
	v_cvt_pk_bf16_f32 v179, v182, v183
	s_waitcnt lgkmcnt(3)
	v_mfma_f32_32x32x16_bf16 v[32:47], v[240:243], v[160:163], v[32:47]
	ds_read_b128 v[218:221], v209 offset:24576
	v_exp_f32_e32 v168, v168
	v_exp_f32_e32 v169, v169
	v_add_f32_e32 v207, v207, v168
	v_add_f32_e32 v207, v207, v169
	s_waitcnt lgkmcnt(3)
	v_mfma_f32_32x32x16_bf16 v[0:15], v[192:195], v[160:163], v[0:15]
	ds_read_b128 v[222:225], v209 offset:28672
	v_cvt_pk_bf16_f32 v164, v168, v169
	v_exp_f32_e32 v170, v170
	v_exp_f32_e32 v171, v171
	v_add_f32_e32 v207, v207, v170
	v_mfma_f32_32x32x16_bf16 v[96:111], v[226:229], v[176:179], v[96:111]
	v_add_f32_e32 v207, v207, v171
	v_cvt_pk_bf16_f32 v165, v170, v171
	v_exp_f32_e32 v172, v172
	v_exp_f32_e32 v173, v173
	v_mfma_f32_32x32x16_bf16 v[80:95], v[230:233], v[176:179], v[80:95]
	v_add_f32_e32 v207, v207, v172
	v_add_f32_e32 v207, v207, v173
	v_cvt_pk_bf16_f32 v166, v172, v173
	v_exp_f32_e32 v174, v174
	v_mfma_f32_32x32x16_bf16 v[48:63], v[240:243], v[176:179], v[48:63]
	v_exp_f32_e32 v175, v175
	v_add_f32_e32 v207, v207, v174
	v_add_f32_e32 v207, v207, v175
	v_cvt_pk_bf16_f32 v167, v174, v175
	v_mfma_f32_32x32x16_bf16 v[16:31], v[192:195], v[176:179], v[16:31]
	v_exp_f32_e32 v184, v184
	v_exp_f32_e32 v185, v185
	v_add_f32_e32 v206, v206, v184
	v_add_f32_e32 v206, v206, v185
	s_waitcnt lgkmcnt(3)
	v_mfma_f32_32x32x16_bf16 v[112:127], v[210:213], v[164:167], v[112:127]
	v_cvt_pk_bf16_f32 v180, v184, v185
	v_exp_f32_e32 v186, v186
	v_exp_f32_e32 v187, v187
	v_add_f32_e32 v206, v206, v186
	s_waitcnt lgkmcnt(2)
	v_mfma_f32_32x32x16_bf16 v[64:79], v[214:217], v[164:167], v[64:79]
	v_add_f32_e32 v206, v206, v187
	v_cvt_pk_bf16_f32 v181, v186, v187
	v_exp_f32_e32 v188, v188
	v_exp_f32_e32 v189, v189
	s_waitcnt lgkmcnt(1)
	v_mfma_f32_32x32x16_bf16 v[32:47], v[218:221], v[164:167], v[32:47]
	v_add_f32_e32 v206, v206, v188
	v_add_f32_e32 v206, v206, v189
	v_cvt_pk_bf16_f32 v182, v188, v189
	v_exp_f32_e32 v190, v190
	s_waitcnt lgkmcnt(0)
	v_mfma_f32_32x32x16_bf16 v[0:15], v[222:225], v[164:167], v[0:15]
	v_exp_f32_e32 v191, v191
	v_add_f32_e32 v206, v206, v190
	v_add_f32_e32 v206, v206, v191
	v_cvt_pk_bf16_f32 v183, v190, v191
